# baseline (speedup 1.0000x reference)
; DEV int tidx() { int t = threadIdx.x; asm volatile("" : "+v"(t)); return t; }
; #define ctr ((int*)(wsp(p) + W_CTR))
; DEV void phase_scan(const Params& p, int layer, int* ctr, char* smem) {
;   int* sitem = (int*)(smem + 78848);
;   for (;;) {
;     __syncthreads();
;     if (tidx() == 0) *sitem = atomicAdd(ctr, 1);
;     __syncthreads();
;     const int item = __builtin_amdgcn_readfirstlane(*sitem);
;     if (item >= 128 + 512) break;
;     gdn_scan_item(p, layer, item, smem);
;   }
; }
.Lsc_fetch:
	s_and_b32 s2, s52, 0x180
	s_cmpk_lg_i32 s2, 0x100
	s_cbranch_scc1 .Lsc_fetch2
	s_mov_b64 s[0:1], -1
	s_movk_i32 s2, 0x280
	s_branch .Lsc_decode
